# DN0-PP0 and DN1-PP1 seams: group barrier with L2 writeback plus waits on the arrival counters of the 1-2 groups whose HDN panel the pp / XB3 tile overlays
# speedup vs baseline: 1.0034x; 1.0034x over previous
.LBB0_1128:
	s_andn2_b64 vcc, exec, s[0:1]
	s_cbranch_vccnz .LBB0_1195
	v_readlane_b32 s0, v249, 4
	v_readlane_b32 s1, v249, 5
	s_cmpk_lt_u32 s1, 0x3e9
	s_mov_b64 s[0:1], -1
	s_cbranch_scc0 .LBB0_1183
	v_readlane_b32 s2, v249, 2
	s_cmpk_eq_i32 s2, 0x100
	s_cbranch_scc0 .Lg5_xcd
	s_waitcnt vmcnt(0)
	s_waitcnt vmcnt(0) lgkmcnt(0)
	s_barrier
	s_mov_b64 s[0:1], exec
	v_readlane_b32 s2, v249, 10
	v_readlane_b32 s3, v249, 11
	s_and_b64 s[2:3], s[0:1], s[2:3]
	s_mov_b64 exec, s[2:3]
	s_cbranch_execz .Lg5_BB0_1004
	s_lshl_b32 s2, s81, 8
	s_and_b32 s2, s2, 0x3f00
	s_mov_b64 s[4:5], exec
	s_add_u32 s2, s82, s2
	s_addc_u32 s3, s83, 0
	buffer_wbl2 sc1

.Lg5_BB0_1003:
	s_or_b64 exec, exec, s[4:5]
	s_and_b32 s4, s81, 7
	s_lshl_b32 s4, s4, 3
	s_bfe_u32 s5, s81, 0x30003
	s_add_i32 s4, s4, s5
	s_lshr_b32 s12, s4, 2
	s_mov_b32 s13, 1
	s_add_i32 s14, s12, 48
	v_mov_b32_e32 v1, 0
	s_mov_b32 s9, 16
	s_mov_b32 s8, 0
.Lg5_xnext:
	s_cmp_eq_u32 s13, 0
	s_cbranch_scc0 .Lg5_xhave
	s_cmp_lt_i32 s14, 0
	s_cbranch_scc1 .Lg5_xdone
	s_mov_b32 s12, s14
	s_mov_b32 s14, -1
	s_mov_b32 s13, 1
.Lg5_xhave:
	s_and_b32 s6, s12, 7
	s_lshl_b32 s6, s6, 3
	s_lshr_b32 s7, s12, 3
	s_or_b32 s6, s6, s7
	s_lshl_b32 s6, s6, 8
	s_add_u32 s6, s6, 0x10000
	s_add_u32 s6, s82, s6
	s_addc_u32 s7, s83, 0
.Lg5_xspin:
	global_load_dword v3, v1, s[6:7] sc1
	s_add_i32 s8, s8, 1
	s_waitcnt vmcnt(0)
	v_cmp_gt_u32_e32 vcc, s9, v3
	s_cmp_lt_u32 s8, 0x80000
	s_cselect_b64 s[10:11], vcc, 0
	s_and_b64 vcc, s[10:11], exec
	s_cbranch_vccnz .Lg5_xspin
	s_add_i32 s12, s12, 1
	s_sub_u32 s13, s13, 1
	s_branch .Lg5_xnext
.Lg5_xdone:
	s_waitcnt vmcnt(0)
	buffer_inv sc1
	s_waitcnt vmcnt(0)

.Lg12_BB0_1003:
	s_or_b64 exec, exec, s[4:5]
	s_and_b32 s4, s81, 7
	s_lshl_b32 s4, s4, 3
	s_bfe_u32 s5, s81, 0x30003
	s_add_i32 s4, s4, s5
	s_lshr_b32 s12, s4, 2
	s_mov_b32 s13, 1
	s_mov_b32 s14, -1
	v_mov_b32_e32 v1, 0
	s_mov_b32 s9, 28
	s_mov_b32 s8, 0
